# scan producer write-out reduction tree (7 packed adds + 1 add per output instead of 17 ops)
# speedup vs baseline: 1.0394x; 1.0009x over previous
.LBB0_1068:
	s_or_b64 exec, exec, s[56:57]
	ds_read_b128 v[34:37], v98
	ds_read_b128 v[80:83], v98 offset:16
	ds_read_b128 v[84:87], v98 offset:32
	ds_read_b128 v[104:107], v98 offset:48
	s_waitcnt lgkmcnt(0)
	v_pk_add_f32 v[34:35], v[34:35], v[36:37]
	v_pk_add_f32 v[80:81], v[80:81], v[82:83]
	v_pk_add_f32 v[84:85], v[84:85], v[86:87]
	v_pk_add_f32 v[104:105], v[104:105], v[106:107]
	v_pk_add_f32 v[34:35], v[34:35], v[80:81]
	v_pk_add_f32 v[84:85], v[84:85], v[104:105]
	s_min_u32 s56, s61, 0x1fb
	s_add_i32 s52, s52, 2
	v_pk_add_f32 v[34:35], v[34:35], v[84:85]
	s_nop 0
	v_add_f32_e32 v22, v34, v35
	v_cndmask_b32_e64 v134, v9, v17, s[4:5]
	v_fma_mixlo_f16 v34, v22, s82, 0
	v_lshl_add_u64 v[22:23], v[10:11], 0, v[134:135]
	v_lshlrev_b64 v[22:23], 10, v[22:23]
	v_lshl_add_u64 v[22:23], v[12:13], 0, v[22:23]
	v_lshl_add_u32 v134, s56, 4, v96
	global_store_short v[22:23], v34, off
	v_lshl_add_u64 v[22:23], s[54:55], 0, v[134:135]
	v_mad_u64_u32 v[36:37], s[56:57], v22, s50, v[18:19]
	v_mad_i32_i24 v37, v23, s50, v37
	v_lshlrev_b64 v[22:23], 10, v[22:23]
	v_lshl_add_u64 v[34:35], v[14:15], 0, v[22:23]
	v_or_b32_e32 v22, v22, v103
	v_lshlrev_b64 v[22:23], 1, v[22:23]
	v_lshl_add_u64 v[38:39], v[42:43], 0, v[22:23]
	v_lshl_add_u64 v[22:23], v[44:45], 0, v[22:23]
	global_load_dwordx2 v[84:85], v[22:23], off
	v_sub_u32_e32 v22, 0x1fff, v134
	v_or_b32_e32 v22, s54, v22
	global_load_dwordx2 v[80:81], v[38:39], off
	v_mad_u64_u32 v[38:39], s[56:57], v22, s50, v[18:19]
	v_mov_b32_e32 v23, s55
	v_mad_i32_i24 v39, s55, v166, v39
	global_load_dwordx2 v[34:35], v[34:35], off
	s_nop 0
	global_load_dwordx2 v[86:87], v[36:37], off offset:1024
	global_load_dwordx2 v[82:83], v[36:37], off offset:2048
	global_load_dwordx2 v[70:71], v[38:39], off offset:1024
	s_nop 0
	global_load_dwordx2 v[36:37], v[38:39], off offset:2048
	v_lshlrev_b64 v[38:39], 10, v[22:23]
	v_lshl_add_u64 v[22:23], v[14:15], 0, v[38:39]
	v_or_b32_e32 v38, v38, v16
	v_lshlrev_b64 v[74:75], 1, v[38:39]
	v_lshl_add_u64 v[38:39], v[42:43], 0, v[74:75]
	v_lshl_add_u64 v[74:75], v[44:45], 0, v[74:75]
	global_load_dwordx2 v[22:23], v[22:23], off
	v_add_u32_e32 v17, 32, v17
	global_load_dwordx2 v[38:39], v[38:39], off
	s_cmpk_gt_u32 s61, 0x1fd
	global_load_dwordx2 v[74:75], v[74:75], off
	s_waitcnt lgkmcnt(0)
	s_barrier
	v_subrev_u32_e32 v9, 32, v9
	s_cbranch_scc1 .LBB0_1050
.LBB0_1069:
	s_waitcnt vmcnt(16)
	v_lshlrev_b32_e32 v116, 16, v72
	v_and_b32_e32 v117, 0xffff0000, v72
	s_waitcnt vmcnt(16)
	v_cvt_f32_f16_e32 v72, v77
	v_lshlrev_b32_e32 v104, 16, v78
	v_and_b32_e32 v105, 0xffff0000, v78
	v_pk_mul_f32 v[108:109], v[0:1], v[116:117]
	v_sub_f32_e32 v78, 1.0, v72
	v_lshlrev_b32_e32 v72, 16, v73
	v_and_b32_e32 v73, 0xffff0000, v73
	v_pk_mul_f32 v[110:111], v[108:109], v[108:109]
	v_pk_mul_f32 v[112:113], v[2:3], v[72:73]
	s_waitcnt vmcnt(15)
	v_lshlrev_b32_e32 v118, 16, v68
	v_and_b32_e32 v119, 0xffff0000, v68
	v_pk_mul_f32 v[114:115], v[112:113], v[112:113]
	v_add_f32_e32 v68, v110, v111
	v_add_f32_e32 v68, v114, v68
	v_add_f32_e32 v68, v115, v68
	v_cvt_f32_f16_sdwa v120, v76 dst_sel:DWORD dst_unused:UNUSED_PAD src0_sel:WORD_1
	v_cvt_f32_f16_sdwa v77, v77 dst_sel:DWORD dst_unused:UNUSED_PAD src0_sel:WORD_1
	v_add_f32_dpp v68, v68, v68 quad_perm:[1,0,3,2] row_mask:0xf bank_mask:0xf bound_ctrl:1
	v_cvt_f32_f16_e32 v76, v76
	v_lshlrev_b32_e32 v106, 16, v79
	v_add_f32_dpp v68, v68, v68 quad_perm:[2,3,0,1] row_mask:0xf bank_mask:0xf bound_ctrl:1
	v_and_b32_e32 v107, 0xffff0000, v79
	v_sub_f32_e32 v79, 1.0, v77
	v_add_f32_dpp v68, v68, v68 row_half_mirror row_mask:0xf bank_mask:0xf bound_ctrl:1
	v_sub_f32_e32 v77, 1.0, v120
	v_lshlrev_b32_e32 v120, 16, v69
	v_add_f32_dpp v68, v68, v68 row_ror:8 row_mask:0xf bank_mask:0xf bound_ctrl:1
	v_max_f32_e32 v68, 0x179abe15, v68
	v_rsq_f32_e32 v68, v68
	v_and_b32_e32 v121, 0xffff0000, v69
	v_sub_f32_e32 v76, 1.0, v76
	v_pk_mul_f32 v[108:109], v[108:109], v[68:69] op_sel_hi:[1,0]
	v_pk_mul_f32 v[110:111], v[112:113], v[68:69] op_sel_hi:[1,0]
	v_pk_mul_f32 v[112:113], v[108:109], v[118:119]
	v_pk_add_f32 v[68:69], v[120:121], -1.0 op_sel_hi:[1,0]
	v_pk_add_f32 v[118:119], v[118:119], -1.0 op_sel_hi:[1,0]
	v_pk_mul_f32 v[114:115], v[110:111], v[120:121]
	v_pk_fma_f32 v[120:121], v[4:5], v[118:119], 1.0 op_sel_hi:[1,1,0]
	v_pk_fma_f32 v[68:69], v[6:7], v[68:69], 1.0 op_sel_hi:[1,1,0]
	v_pk_mul_f32 v[116:117], v[120:121], v[116:117]
	v_pk_mul_f32 v[118:119], v[68:69], v[72:73]
	ds_write_b128 v61, v[76:79] offset:41984
	ds_write_b128 v61, v[108:111] offset:46080
	ds_write_b128 v61, v[112:115] offset:50176
	ds_write_b128 v61, v[116:119] offset:54272
	ds_write_b128 v61, v[104:107] offset:58368
	s_and_saveexec_b64 s[56:57], s[6:7]
	v_lshlrev_b32_e32 v76, 16, v24
	v_and_b32_e32 v77, 0xffff0000, v24
	v_lshlrev_b32_e32 v78, 16, v25
	v_and_b32_e32 v79, 0xffff0000, v25
	ds_write_b128 v88, v[76:79] offset:62464
	s_or_b64 exec, exec, s[56:57]
	s_waitcnt vmcnt(11)
	v_cvt_f32_f16_e32 v24, v32
	v_cvt_f32_f16_e32 v25, v33
	v_lshlrev_b32_e32 v68, 16, v26
	v_and_b32_e32 v69, 0xffff0000, v26
	v_cvt_f32_f16_sdwa v26, v33 dst_sel:DWORD dst_unused:UNUSED_PAD src0_sel:WORD_1
	v_lshlrev_b32_e32 v76, 16, v30
	v_and_b32_e32 v77, 0xffff0000, v30
	v_lshlrev_b32_e32 v78, 16, v31
	v_and_b32_e32 v79, 0xffff0000, v31
	v_cvt_f32_f16_sdwa v31, v32 dst_sel:DWORD dst_unused:UNUSED_PAD src0_sel:WORD_1
	v_sub_f32_e32 v32, 1.0, v25
	v_sub_f32_e32 v30, 1.0, v24
	v_lshlrev_b32_e32 v108, 16, v27
	v_and_b32_e32 v109, 0xffff0000, v27
	v_pk_mul_f32 v[24:25], v[0:1], v[68:69]
	v_sub_f32_e32 v33, 1.0, v26
	v_pk_mul_f32 v[26:27], v[24:25], v[24:25]
	v_pk_mul_f32 v[104:105], v[2:3], v[108:109]
	v_add_f32_e32 v26, v26, v27
	v_pk_mul_f32 v[106:107], v[104:105], v[104:105]
	s_waitcnt vmcnt(10)
	v_lshlrev_b32_e32 v72, 16, v28
	v_add_f32_e32 v26, v106, v26
	v_add_f32_e32 v26, v107, v26
	v_and_b32_e32 v73, 0xffff0000, v28
	v_lshlrev_b32_e32 v28, 16, v29
	v_add_f32_dpp v26, v26, v26 quad_perm:[1,0,3,2] row_mask:0xf bank_mask:0xf bound_ctrl:1
	v_and_b32_e32 v29, 0xffff0000, v29
	v_sub_f32_e32 v31, 1.0, v31
	v_add_f32_dpp v26, v26, v26 quad_perm:[2,3,0,1] row_mask:0xf bank_mask:0xf bound_ctrl:1
	s_nop 1
	v_add_f32_dpp v26, v26, v26 row_half_mirror row_mask:0xf bank_mask:0xf bound_ctrl:1
	s_nop 1
	v_add_f32_dpp v26, v26, v26 row_ror:8 row_mask:0xf bank_mask:0xf bound_ctrl:1
	v_max_f32_e32 v26, 0x179abe15, v26
	v_rsq_f32_e32 v26, v26
	s_nop 0
	v_pk_mul_f32 v[24:25], v[24:25], v[26:27] op_sel_hi:[1,0]
	v_pk_mul_f32 v[26:27], v[104:105], v[26:27] op_sel_hi:[1,0]
	v_pk_mul_f32 v[104:105], v[24:25], v[72:73]
	v_pk_mul_f32 v[106:107], v[26:27], v[28:29]
	v_pk_add_f32 v[28:29], v[28:29], -1.0 op_sel_hi:[1,0]
	v_pk_add_f32 v[72:73], v[72:73], -1.0 op_sel_hi:[1,0]
	v_pk_fma_f32 v[28:29], v[6:7], v[28:29], 1.0 op_sel_hi:[1,1,0]
	v_pk_fma_f32 v[72:73], v[4:5], v[72:73], 1.0 op_sel_hi:[1,1,0]
	v_pk_mul_f32 v[110:111], v[28:29], v[108:109]
	v_pk_mul_f32 v[108:109], v[72:73], v[68:69]
	ds_write_b128 v61, v[30:33] offset:62976
	ds_write_b128 v89, v[24:27]
	ds_write_b128 v90, v[104:107]
	ds_write_b128 v91, v[108:111]
	ds_write_b128 v92, v[76:79]
	s_and_saveexec_b64 s[56:57], s[6:7]
	v_lshlrev_b32_e32 v24, 16, v20
	v_and_b32_e32 v25, 0xffff0000, v20
	v_lshlrev_b32_e32 v26, 16, v21
	v_and_b32_e32 v27, 0xffff0000, v21
	ds_write_b128 v97, v[24:27] offset:20480
	s_or_b64 exec, exec, s[56:57]
	ds_read_b128 v[24:27], v94
	ds_read_b128 v[28:31], v94 offset:16
	ds_read_b128 v[76:79], v94 offset:32
	ds_read_b128 v[104:107], v94 offset:48
	s_waitcnt lgkmcnt(0)
	v_pk_add_f32 v[24:25], v[24:25], v[26:27]
	v_pk_add_f32 v[28:29], v[28:29], v[30:31]
	v_pk_add_f32 v[76:77], v[76:77], v[78:79]
	v_pk_add_f32 v[104:105], v[104:105], v[106:107]
	v_pk_add_f32 v[24:25], v[24:25], v[28:29]
	v_pk_add_f32 v[76:77], v[76:77], v[104:105]
	s_min_u32 s56, s52, 1
	s_lshl_b32 s56, s56, 4
	s_add_i32 s61, s61, 2
	s_waitcnt vmcnt(6)
	v_pk_add_f32 v[24:25], v[24:25], v[76:77]
	s_nop 0
	v_add_f32_e32 v20, v24, v25
	v_lshlrev_b32_e32 v104, 16, v86
	v_add_u32_e32 v24, s56, v9
	v_subrev_u32_e32 v21, s56, v17
	v_cndmask_b32_e64 v134, v24, v21, s[4:5]
	v_fma_mixlo_f16 v24, v20, s82, 0
	v_lshl_add_u64 v[20:21], v[10:11], 0, v[134:135]
	v_lshlrev_b64 v[20:21], 10, v[20:21]
	s_min_u32 s56, s61, 0x1fc
	v_lshl_add_u64 v[20:21], v[12:13], 0, v[20:21]
	v_lshl_add_u32 v134, s56, 4, v95
	global_store_short v[20:21], v24, off
	v_lshl_add_u64 v[20:21], s[54:55], 0, v[134:135]
	v_mad_u64_u32 v[26:27], s[56:57], v20, s50, v[18:19]
	v_mad_i32_i24 v27, v21, s50, v27
	v_lshlrev_b64 v[20:21], 10, v[20:21]
	v_lshl_add_u64 v[24:25], v[14:15], 0, v[20:21]
	v_or_b32_e32 v20, v20, v103
	v_lshlrev_b64 v[20:21], 1, v[20:21]
	v_lshl_add_u64 v[28:29], v[42:43], 0, v[20:21]
	v_lshl_add_u64 v[20:21], v[44:45], 0, v[20:21]
	global_load_dwordx2 v[76:77], v[20:21], off
	v_sub_u32_e32 v20, 0x1fff, v134
	v_or_b32_e32 v20, s54, v20
	global_load_dwordx2 v[68:69], v[28:29], off
	v_mad_u64_u32 v[28:29], s[56:57], v20, s50, v[18:19]
	v_mov_b32_e32 v21, s55
	v_mad_i32_i24 v29, s55, v166, v29
	global_load_dwordx2 v[24:25], v[24:25], off
	s_nop 0
	global_load_dwordx2 v[78:79], v[26:27], off offset:1024
	global_load_dwordx2 v[72:73], v[26:27], off offset:2048
	global_load_dwordx2 v[30:31], v[28:29], off offset:1024
	s_nop 0
	global_load_dwordx2 v[26:27], v[28:29], off offset:2048
	v_lshlrev_b64 v[28:29], 10, v[20:21]
	v_lshl_add_u64 v[20:21], v[14:15], 0, v[28:29]
	v_or_b32_e32 v28, v28, v16
	v_lshlrev_b64 v[32:33], 1, v[28:29]
	v_lshl_add_u64 v[28:29], v[42:43], 0, v[32:33]
	v_lshl_add_u64 v[32:33], v[44:45], 0, v[32:33]
	global_load_dwordx2 v[20:21], v[20:21], off
	v_and_b32_e32 v105, 0xffff0000, v86
	global_load_dwordx2 v[28:29], v[28:29], off
	v_lshlrev_b32_e32 v106, 16, v87
	global_load_dwordx2 v[32:33], v[32:33], off
	v_and_b32_e32 v107, 0xffff0000, v87
	s_waitcnt vmcnt(17)
	v_cvt_f32_f16_e32 v108, v84
	s_waitcnt vmcnt(16)
	v_lshlrev_b32_e32 v86, 16, v82
	v_and_b32_e32 v87, 0xffff0000, v82
	v_cvt_f32_f16_e32 v82, v85
	v_cvt_f32_f16_sdwa v120, v84 dst_sel:DWORD dst_unused:UNUSED_PAD src0_sel:WORD_1
	v_lshlrev_b32_e32 v118, 16, v83
	v_and_b32_e32 v119, 0xffff0000, v83
	v_sub_f32_e32 v84, 1.0, v82
	v_sub_f32_e32 v82, 1.0, v108
	v_pk_mul_f32 v[108:109], v[0:1], v[86:87]
	v_pk_mul_f32 v[112:113], v[2:3], v[118:119]
	v_pk_mul_f32 v[110:111], v[108:109], v[108:109]
	s_waitcnt vmcnt(16)
	v_lshlrev_b32_e32 v116, 16, v80
	v_and_b32_e32 v117, 0xffff0000, v80
	v_pk_mul_f32 v[114:115], v[112:113], v[112:113]
	v_add_f32_e32 v80, v110, v111
	v_add_f32_e32 v80, v114, v80
	v_add_f32_e32 v80, v115, v80
	v_cvt_f32_f16_sdwa v85, v85 dst_sel:DWORD dst_unused:UNUSED_PAD src0_sel:WORD_1
	s_waitcnt lgkmcnt(0)
	s_barrier
	v_sub_f32_e32 v83, 1.0, v120
	v_add_f32_dpp v80, v80, v80 quad_perm:[1,0,3,2] row_mask:0xf bank_mask:0xf bound_ctrl:1
	v_lshlrev_b32_e32 v120, 16, v81
	v_and_b32_e32 v121, 0xffff0000, v81
	v_add_f32_dpp v80, v80, v80 quad_perm:[2,3,0,1] row_mask:0xf bank_mask:0xf bound_ctrl:1
	v_sub_f32_e32 v85, 1.0, v85
	s_nop 0
	v_add_f32_dpp v80, v80, v80 row_half_mirror row_mask:0xf bank_mask:0xf bound_ctrl:1
	s_nop 1
	v_add_f32_dpp v80, v80, v80 row_ror:8 row_mask:0xf bank_mask:0xf bound_ctrl:1
	v_max_f32_e32 v80, 0x179abe15, v80
	v_rsq_f32_e32 v80, v80
	s_nop 0
	v_pk_mul_f32 v[108:109], v[108:109], v[80:81] op_sel_hi:[1,0]
	v_pk_mul_f32 v[110:111], v[112:113], v[80:81] op_sel_hi:[1,0]
	v_pk_mul_f32 v[112:113], v[108:109], v[116:117]
	v_pk_add_f32 v[80:81], v[120:121], -1.0 op_sel_hi:[1,0]
	v_pk_add_f32 v[116:117], v[116:117], -1.0 op_sel_hi:[1,0]
	v_pk_fma_f32 v[80:81], v[6:7], v[80:81], 1.0 op_sel_hi:[1,1,0]
	v_pk_fma_f32 v[116:117], v[4:5], v[116:117], 1.0 op_sel_hi:[1,1,0]
	v_pk_mul_f32 v[114:115], v[110:111], v[120:121]
	v_pk_mul_f32 v[118:119], v[80:81], v[118:119]
	v_pk_mul_f32 v[116:117], v[116:117], v[86:87]
	ds_write_b128 v61, v[82:85]
	ds_write_b128 v61, v[108:111] offset:4096
	ds_write_b128 v61, v[112:115] offset:8192
	ds_write_b128 v61, v[116:119] offset:12288
	ds_write_b128 v61, v[104:107] offset:16384
	s_and_saveexec_b64 s[56:57], s[6:7]
	v_lshlrev_b32_e32 v80, 16, v34
	v_and_b32_e32 v81, 0xffff0000, v34
	v_lshlrev_b32_e32 v82, 16, v35
	v_and_b32_e32 v83, 0xffff0000, v35
	ds_write_b128 v88, v[80:83] offset:20480
	s_or_b64 exec, exec, s[56:57]
	s_waitcnt vmcnt(11)
	v_cvt_f32_f16_e32 v34, v74
	v_cvt_f32_f16_e32 v35, v75
	v_lshlrev_b32_e32 v80, 16, v70
	v_and_b32_e32 v81, 0xffff0000, v70
	v_lshlrev_b32_e32 v82, 16, v71
	v_and_b32_e32 v83, 0xffff0000, v71
	v_lshlrev_b32_e32 v70, 16, v36
	v_and_b32_e32 v71, 0xffff0000, v36
	v_cvt_f32_f16_sdwa v36, v75 dst_sel:DWORD dst_unused:UNUSED_PAD src0_sel:WORD_1
	v_sub_f32_e32 v86, 1.0, v35
	v_sub_f32_e32 v84, 1.0, v34
	v_lshlrev_b32_e32 v108, 16, v37
	v_and_b32_e32 v109, 0xffff0000, v37
	v_pk_mul_f32 v[34:35], v[0:1], v[70:71]
	v_sub_f32_e32 v87, 1.0, v36
	v_pk_mul_f32 v[36:37], v[34:35], v[34:35]
	v_pk_mul_f32 v[104:105], v[2:3], v[108:109]
	v_add_f32_e32 v36, v36, v37
	v_pk_mul_f32 v[106:107], v[104:105], v[104:105]
	v_cvt_f32_f16_sdwa v85, v74 dst_sel:DWORD dst_unused:UNUSED_PAD src0_sel:WORD_1
	v_add_f32_e32 v36, v106, v36
	v_add_f32_e32 v36, v107, v36
	v_lshlrev_b32_e32 v74, 16, v38
	v_and_b32_e32 v75, 0xffff0000, v38
	v_add_f32_dpp v36, v36, v36 quad_perm:[1,0,3,2] row_mask:0xf bank_mask:0xf bound_ctrl:1
	v_lshlrev_b32_e32 v38, 16, v39
	v_and_b32_e32 v39, 0xffff0000, v39
	v_add_f32_dpp v36, v36, v36 quad_perm:[2,3,0,1] row_mask:0xf bank_mask:0xf bound_ctrl:1
	v_sub_f32_e32 v85, 1.0, v85
	s_nop 0
	v_add_f32_dpp v36, v36, v36 row_half_mirror row_mask:0xf bank_mask:0xf bound_ctrl:1
	s_nop 1
	v_add_f32_dpp v36, v36, v36 row_ror:8 row_mask:0xf bank_mask:0xf bound_ctrl:1
	v_max_f32_e32 v36, 0x179abe15, v36
	v_rsq_f32_e32 v36, v36
	s_nop 0
	v_pk_mul_f32 v[34:35], v[34:35], v[36:37] op_sel_hi:[1,0]
	v_pk_mul_f32 v[36:37], v[104:105], v[36:37] op_sel_hi:[1,0]
	v_pk_mul_f32 v[104:105], v[34:35], v[74:75]
	v_pk_mul_f32 v[106:107], v[36:37], v[38:39]
	v_pk_add_f32 v[38:39], v[38:39], -1.0 op_sel_hi:[1,0]
	v_pk_add_f32 v[74:75], v[74:75], -1.0 op_sel_hi:[1,0]
	v_pk_fma_f32 v[38:39], v[6:7], v[38:39], 1.0 op_sel_hi:[1,1,0]
	v_pk_fma_f32 v[74:75], v[4:5], v[74:75], 1.0 op_sel_hi:[1,1,0]
	v_pk_mul_f32 v[110:111], v[38:39], v[108:109]
	v_pk_mul_f32 v[108:109], v[74:75], v[70:71]
	ds_write_b128 v61, v[84:87] offset:20992
	ds_write_b128 v61, v[34:37] offset:25088
	ds_write_b128 v61, v[104:107] offset:29184
	ds_write_b128 v61, v[108:111] offset:33280
	ds_write_b128 v61, v[80:83] offset:37376
	s_and_saveexec_b64 s[56:57], s[6:7]
	s_cbranch_execz .LBB0_1068
	v_lshlrev_b32_e32 v34, 16, v22
	v_and_b32_e32 v35, 0xffff0000, v22
	v_lshlrev_b32_e32 v36, 16, v23
	v_and_b32_e32 v37, 0xffff0000, v23
	ds_write_b128 v88, v[34:37] offset:41472
	s_branch .LBB0_1068
